# compressed-attention phase: per-head query fragments prefetched one head ahead into spare registers; gate load issued first with a counted wait
# baseline (speedup 1.0000x reference)
; #define LAS __attribute__((address_space(3)))
; __device__ __forceinline__ void item_attn_cmp(LAS unsigned char* lds, const bf16_t* qkv, const bf16_t* KC, bf16_t* Yb, unsigned* selm, int it) {
;     int tid_ = threadIdx.x; asm volatile("" : "+v"(tid_));
;     const int tid = tid_, lane = tid & 63, wid = tid >> 6, c = lane & 15, g = lane >> 4;
;     const int q16 = it & 15, gk = (it >> 4) & 1, b = it >> 5; const int q0 = q16 * 128;
;     LAS unsigned char* Ks = lds + CMP_KS; LAS unsigned char* Vt = lds + CMP_VT;
;     const bf16_t* kc = KC + (((size_t)0 * 32 + b) * 2 + gk) * 128 * 64; const bf16_t* vc = KC + (((size_t)1 * 32 + b) * 2 + gk) * 128 * 64;
;     __syncthreads();
; #pragma unroll
;     for (int r = 0; r < 2; ++r) { const int e = tid + 512 * r; const int key = e >> 3, ch = e & 7;
;         u32x4 kv = (u32x4){0u, 0u, 0u, 0u}, vv = kv;
;         if (key < 127) { kv = *(const u32x4*)(kc + key * 64 + ch * 8); vv = *(const u32x4*)(vc + key * 64 + ch * 8); }
;         *(LAS u32x4*)(Ks + key * CMP_KPB + ch * 16) = kv; *(LAS u32x4*)(Vt + key * CMP_KPB + ch * 16) = vv; }
;     __syncthreads();
;     const int t = q0 + wid * 16 + c; const size_t row = (size_t)b * SEQ + t;
;     float psum[8][4];
; #pragma unroll
;     for (int nt = 0; nt < 8; ++nt)
; #pragma unroll
;         for (int j = 0; j < 4; ++j) psum[nt][j] = 0.f;
; #pragma unroll 1
.LBB0_358:
	s_or_b64 exec, exec, s[4:5]
	s_lshr_b32 s4, s26, 4
	s_and_b32 s15, s4, 1
	v_mad_u64_u32 v[2:3], s[4:5], v16, s84, v[20:21]
	s_lshl_b32 s6, s26, 7
	s_waitcnt vmcnt(1)
	ds_write_b128 v2, v[12:15]
	s_waitcnt vmcnt(0)
	ds_write_b128 v2, v[8:11] offset:18432
	v_ashrrev_i32_e32 v210, 2, v1
	v_lshlrev_b32_e32 v10, 3, v1
	v_and_b32_e32 v209, 15, v1
	s_and_b32 s4, s6, 0x780
	v_and_b32_e32 v3, -16, v210
	v_and_b32_e32 v10, 24, v10
	v_add_u32_e32 v211, s4, v3
	v_bfe_u32 v168, v1, 4, 2
	v_and_b32_e32 v72, 48, v1
	v_add_u32_e32 v78, 0, v10
	v_mul_u32_u24_e32 v10, 0x90, v209
	v_or_b32_e32 v2, v211, v209
	v_add3_u32 v68, 0, v10, v72
	v_lshlrev_b32_e32 v10, 6, v168
	v_subrev_u32_e32 v8, 31, v2
	v_or_b32_e32 v11, 48, v10
	v_cmp_gt_i32_e64 s[40:41], v11, v8
	v_or_b32_e32 v11, 0x100, v10
	v_cmp_gt_i32_e64 s[44:45], v11, v8
	v_or_b32_e32 v11, 16, v10
	v_cmp_gt_i32_e64 s[46:47], v11, v8
	v_or_b32_e32 v11, 32, v10
	v_or_b32_e32 v12, 0x110, v10
	v_cmp_gt_i32_e64 s[50:51], v11, v8
	v_or_b32_e32 v11, 0x130, v10
	v_cmp_gt_i32_e64 s[48:49], v12, v8
	v_or_b32_e32 v12, 0x120, v10
	v_cmp_gt_i32_e64 s[54:55], v11, v8
	v_or_b32_e32 v11, 0x200, v10
	v_cmp_gt_i32_e64 s[52:53], v12, v8
	v_or_b32_e32 v12, 0x300, v10
	v_cmp_gt_i32_e64 s[56:57], v11, v8
	v_or_b32_e32 v11, 0x210, v10
	v_cmp_gt_i32_e64 s[58:59], v12, v8
	v_or_b32_e32 v12, 0x310, v10
	v_cmp_gt_i32_e64 s[60:61], v11, v8
	v_or_b32_e32 v11, 0x220, v10
	v_cmp_gt_i32_e64 s[62:63], v12, v8
	v_or_b32_e32 v12, 0x320, v10
	v_cmp_gt_i32_e64 s[64:65], v11, v8
	v_or_b32_e32 v11, 0x230, v10
	v_cmp_gt_i32_e64 s[66:67], v12, v8
	v_or_b32_e32 v12, 0x330, v10
	v_cmp_gt_i32_e64 s[68:69], v11, v8
	v_or_b32_e32 v11, 0x400, v10
	v_cmp_gt_i32_e64 s[70:71], v12, v8
	v_or_b32_e32 v12, 0x500, v10
	v_cmp_gt_i32_e64 s[72:73], v11, v8
	v_or_b32_e32 v11, 0x410, v10
	v_cmp_gt_i32_e64 s[74:75], v12, v8
	v_or_b32_e32 v12, 0x510, v10
	v_cmp_gt_i32_e64 s[76:77], v11, v8
	v_or_b32_e32 v11, 0x420, v10
	v_cmp_lt_i32_e32 vcc, v223, v218
	v_cmp_gt_i32_e64 s[78:79], v12, v8
	v_or_b32_e32 v12, 0x520, v10
	v_cmp_gt_i32_e64 s[80:81], v11, v8
	v_or_b32_e32 v11, 0x430, v10
	v_cndmask_b32_e32 v9, v217, v223, vcc
	v_cmp_lt_i32_e32 vcc, v224, v218
	v_cmp_gt_i32_e64 s[82:83], v12, v8
	v_or_b32_e32 v12, 0x530, v10
	v_cmp_gt_i32_e64 s[84:85], v11, v8
	v_or_b32_e32 v11, 0x600, v10
	v_lshlrev_b32_e32 v169, 2, v9
	v_cndmask_b32_e32 v9, v217, v224, vcc
	v_cmp_gt_i32_e64 s[86:87], v12, v8
	v_or_b32_e32 v12, 0x700, v10
	v_cmp_gt_i32_e64 s[88:89], v11, v8
	v_or_b32_e32 v11, 0x610, v10
	v_lshlrev_b32_e32 v208, 2, v9
	v_bfe_u32 v9, v1, 2, 2
	v_cmp_gt_i32_e64 s[90:91], v12, v8
	v_or_b32_e32 v12, 0x710, v10
	v_cmp_gt_i32_e64 s[92:93], v11, v8
	v_or_b32_e32 v11, 0x620, v10
	v_lshl_or_b32 v9, v168, 2, v9
	v_cmp_gt_i32_e64 s[42:43], v10, v8
	v_cmp_gt_i32_e64 s[94:95], v12, v8
	v_or_b32_e32 v12, 0x720, v10
	v_cmp_gt_i32_e64 s[96:97], v11, v8
	v_or_b32_e32 v11, 0x630, v10
	v_or_b32_e32 v10, 0x730, v10
	s_waitcnt lgkmcnt(0)
	s_barrier
	v_cmp_gt_i32_e64 s[4:5], v12, v8
	v_cmp_gt_i32_e64 s[6:7], v11, v8
	v_cmp_gt_i32_e64 s[8:9], v10, v8
	v_mul_u32_u24_e32 v79, 0x90, v9
	ds_read_b128 v[8:11], v68
	ds_read_b128 v[12:15], v68 offset:64
	ds_read_b128 v[16:19], v68 offset:2304
	ds_read_b128 v[20:23], v68 offset:2368
	ds_read_b128 v[24:27], v68 offset:4608
	ds_read_b128 v[28:31], v68 offset:4672
	ds_read_b128 v[32:35], v68 offset:6912
	ds_read_b128 v[36:39], v68 offset:6976
	ds_read_b128 v[40:43], v68 offset:9216
	ds_read_b128 v[44:47], v68 offset:9280
	ds_read_b128 v[48:51], v68 offset:11520
	ds_read_b128 v[52:55], v68 offset:11584
	ds_read_b128 v[56:59], v68 offset:13824
	ds_read_b128 v[60:63], v68 offset:13888
	ds_read_b128 v[64:67], v68 offset:16128
	ds_read_b128 v[68:71], v68 offset:16192
	s_and_b32 s13, s36, 0x780
	s_lshl_b32 s16, s15, 9
	s_mul_i32 vcc_hi, s0, 0xe18000
	s_mul_hi_i32 vcc_lo, s0, 0xe18000
	s_add_u32 s10, vcc_hi, 0xc001c00
	s_addc_u32 s11, vcc_lo, 0
	v_add_u32_e32 v73, s13, v3
	v_or_b32_e32 v74, v73, v209
	v_mov_b64_e32 v[76:77], s[10:11]
	s_movk_i32 s13, 0x1c30
	v_mad_i64_i32 v[172:173], s[10:11], v74, s13, v[76:77]
	s_or_b32 s10, vcc_hi, s16
	s_nop 0
	v_mov_b32_e32 v76, s10
	v_mov_b32_e32 v77, vcc_lo
	v_ashrrev_i32_e32 v75, 31, v74
	v_mad_i64_i32 v[76:77], s[10:11], v74, s13, v[76:77]
	v_mov_b32_e32 v73, v0
	v_lshl_add_u64 v[180:181], v[76:77], 0, v[72:73]
	s_lshl_b64 s[0:1], s[0:1], 21
	v_lshlrev_b64 v[72:73], 10, v[74:75]
	v_lshl_add_u64 v[184:185], s[0:1], 0, v[72:73]
	v_or_b32_e32 v72, s16, v184
	v_lshlrev_b32_e32 v73, 1, v1
	v_lshrrev_b32_e32 v74, 1, v1
	v_readlane_b32 s16, v252, 4
	v_and_b32_e32 v73, 32, v73
	v_and_b32_e32 v74, 16, v74
	v_mov_b32_e32 v170, 0
	v_readlane_b32 s18, v252, 6
	v_and_b32_e32 v212, 63, v1
	v_lshl_or_b32 v172, s15, 3, v172
	v_or3_b32 v184, v72, v73, v74
	s_mov_b32 s13, 4
	v_add_u32_e32 v213, v78, v79
	v_mov_b32_e32 v171, v170
	v_mov_b32_e32 v174, v170
	v_mov_b32_e32 v175, v170
	v_mov_b32_e32 v176, v170
	v_mov_b32_e32 v177, v170
	v_mov_b32_e32 v178, v170
	v_mov_b32_e32 v179, v170
	v_mov_b32_e32 v182, v170
	v_mov_b32_e32 v183, v170
	v_mov_b32_e32 v186, v170
	v_mov_b32_e32 v187, v170
	v_mov_b32_e32 v188, v170
	v_mov_b32_e32 v189, v170
	v_mov_b32_e32 v190, v170
	v_mov_b32_e32 v191, v170
	v_mov_b32_e32 v192, v170
	v_mov_b32_e32 v193, v170
	v_mov_b32_e32 v194, v170
	v_mov_b32_e32 v195, v170
	v_mov_b32_e32 v196, v170
	v_mov_b32_e32 v197, v170
	v_mov_b32_e32 v198, v170
	v_mov_b32_e32 v199, v170
	v_mov_b32_e32 v200, v170
	v_mov_b32_e32 v201, v170
	v_mov_b32_e32 v202, v170
	v_mov_b32_e32 v203, v170
	v_mov_b32_e32 v204, v170
	v_mov_b32_e32 v205, v170
	v_mov_b32_e32 v206, v170
	v_mov_b32_e32 v207, v170
	v_readlane_b32 s20, v252, 8
	v_readlane_b32 s21, v252, 9
	s_mov_b32 s15, 0xf149f2ca
	s_brev_b32 s16, 48
	s_mov_b32 s18, 0x3e000000
	v_readlane_b32 s17, v252, 5
	v_readlane_b32 s19, v252, 7
	v_readlane_b32 s22, v252, 10
	v_readlane_b32 s23, v252, 11
	s_nop 1
	v_lshl_add_u64 v[248:249], s[20:21], 0, v[180:181]
	v_add_co_u32_e32 v248, vcc, s16, v248
	v_addc_co_u32_e32 v249, vcc, 0, v249, vcc
	global_load_dword v6, v[248:249], off offset:1600
	global_load_dword v215, v[248:249], off offset:1604
	global_load_dword v225, v[248:249], off offset:1608
	global_load_dword v247, v[248:249], off offset:1612
	global_load_dwordx4 v[248:251], v[248:249], off offset:1536
	v_lshl_add_u64 v[180:181], v[180:181], 0, s[30:31]
	s_waitcnt vmcnt(0)
; #define LAS __attribute__((address_space(3)))
; __device__ __forceinline__ float bf2f(unsigned short u) { return __uint_as_float((unsigned)u << 16); }
; __device__ __forceinline__ float sigmoidf_(float x) { return fast_rcp(1.f + __expf(-x)); }
; #define MFMA16(a, b, c) __builtin_amdgcn_mfma_f32_16x16x32_bf16((a), (b), (c), 0, 0, 0)
; __device__ __forceinline__ void item_attn_cmp(LAS unsigned char* lds, const bf16_t* qkv, const bf16_t* KC, bf16_t* Yb, unsigned* selm, int it) {
;     ...
;     for (int hh = 0; hh < 4; ++hh) {
;         const int h = gk * 4 + hh;
;         const bf16x8 qf0 = *(const bf16x8*)(qkv + row * QP + C_BQ + h * 64 + g * 8), qf1 = *(const bf16x8*)(qkv + row * QP + C_BQ + h * 64 + 32 + g * 8);
;         f32x4 s[8]; float mx = -1e30f;
; #pragma unroll
;         for (int nt = 0; nt < 8; ++nt) { const bf16x8 kf0 = *(const LAS bf16x8*)(Ks + (16 * nt + c) * CMP_KPB + g * 16), kf1 = *(const LAS bf16x8*)(Ks + (16 * nt + c) * CMP_KPB + 64 + g * 16);
;             f32x4 z = (f32x4){0.f, 0.f, 0.f, 0.f}; z = MFMA16(kf0, qf0, z); z = MFMA16(kf1, qf1, z);
; #pragma unroll
;             for (int j = 0; j < 4; ++j) { const int n = 16 * nt + 4 * g + j; const bool valid = (16 * n + 31) <= t; const float lg = valid ? z[j] * 0.125f : -1e30f; z[j] = lg; mx = fmaxf(mx, lg); }
;             s[nt] = z; }
;     ...
;         const float g0 = sigmoidf_(bf2f(qkv[row * QP + C_BG + h]));
.LBB0_359:
	s_nop 0
	s_waitcnt vmcnt(2)
	v_mov_b32_e32 v124, v248
	v_mov_b32_e32 v125, v249
	v_mov_b32_e32 v126, v250
	v_mov_b32_e32 v127, v251
	v_mov_b32_e32 v164, v6
	v_mov_b32_e32 v165, v215
	v_mov_b32_e32 v166, v225
	v_mov_b32_e32 v167, v247
	v_lshl_add_u64 v[78:79], s[20:21], 0, v[180:181]
	v_add_co_u32_e32 v128, vcc, s16, v78
	ds_read_b64_tr_b16 v[74:75], v213 offset:20736
	ds_read_b64_tr_b16 v[72:73], v213 offset:18432
	ds_read_b64_tr_b16 v[80:81], v213 offset:18464
	ds_read_b64_tr_b16 v[82:83], v213 offset:20768
	ds_read_b64_tr_b16 v[76:77], v213 offset:18496
	v_addc_co_u32_e32 v129, vcc, 0, v79, vcc
	v_lshl_add_u64 v[228:229], s[20:21], 0, v[172:173]
	global_load_ushort v228, v[228:229], off
	global_load_dwordx4 v[248:251], v[128:129], off offset:1536
	ds_read_b64_tr_b16 v[78:79], v213 offset:20800
	ds_read_b64_tr_b16 v[120:121], v213 offset:18528
	ds_read_b64_tr_b16 v[122:123], v213 offset:20832
	ds_read_b64_tr_b16 v[116:117], v213 offset:23040
	ds_read_b64_tr_b16 v[118:119], v213 offset:25344
	ds_read_b64_tr_b16 v[112:113], v213 offset:23072
	ds_read_b64_tr_b16 v[114:115], v213 offset:25376
	ds_read_b64_tr_b16 v[108:109], v213 offset:23104
	ds_read_b64_tr_b16 v[110:111], v213 offset:25408
	ds_read_b64_tr_b16 v[104:105], v213 offset:23136
	ds_read_b64_tr_b16 v[106:107], v213 offset:25440
	ds_read_b64_tr_b16 v[100:101], v213 offset:27648
	ds_read_b64_tr_b16 v[102:103], v213 offset:29952
	ds_read_b64_tr_b16 v[96:97], v213 offset:27680
	ds_read_b64_tr_b16 v[98:99], v213 offset:29984
	ds_read_b64_tr_b16 v[92:93], v213 offset:27712
	ds_read_b64_tr_b16 v[94:95], v213 offset:30016
	ds_read_b64_tr_b16 v[88:89], v213 offset:27744
	ds_read_b64_tr_b16 v[90:91], v213 offset:30048
	ds_read_b64_tr_b16 v[84:85], v213 offset:32256
	ds_read_b64_tr_b16 v[86:87], v213 offset:34560
	global_load_dword v6, v[128:129], off offset:1600
	global_load_dword v215, v[128:129], off offset:1604
	global_load_dword v225, v[128:129], off offset:1608
	global_load_dword v247, v[128:129], off offset:1612
	v_lshl_add_u64 v[230:231], s[20:21], 0, v[184:185]
	s_mov_b32 s0, 0x38400000
	s_add_i32 s13, s13, -1
	v_lshl_add_u64 v[172:173], v[172:173], 0, 2
	v_lshl_add_u64 v[180:181], v[180:181], 0, s[30:31]
	v_lshl_add_u64 v[184:185], v[184:185], 0, s[30:31]
	s_cmp_eq_u32 s13, 0
	s_waitcnt lgkmcnt(14)
	v_mfma_f32_16x16x32_bf16 v[130:133], v[16:19], v[124:127], 0
	v_mfma_f32_16x16x32_bf16 v[160:163], v[8:11], v[124:127], 0
	v_mfma_f32_16x16x32_bf16 v[156:159], v[24:27], v[124:127], 0
	v_mfma_f32_16x16x32_bf16 v[152:155], v[32:35], v[124:127], 0
	v_mfma_f32_16x16x32_bf16 v[144:147], v[40:43], v[124:127], 0
	v_mfma_f32_16x16x32_bf16 v[148:151], v[48:51], v[124:127], 0
	v_mfma_f32_16x16x32_bf16 v[136:139], v[56:59], v[124:127], 0
	v_mfma_f32_16x16x32_bf16 v[140:143], v[64:67], v[124:127], 0
	ds_read_b64_tr_b16 v[124:125], v213 offset:32288
	ds_read_b64_tr_b16 v[126:127], v213 offset:34592
	ds_read_b64_tr_b16 v[128:129], v213 offset:32320
	v_mfma_f32_16x16x32_bf16 v[232:235], v[20:23], v[164:167], v[130:133]
	s_nop 2
	ds_read_b64_tr_b16 v[130:131], v213 offset:34624
	ds_read_b64_tr_b16 v[132:133], v213 offset:32352
	ds_read_b64_tr_b16 v[134:135], v213 offset:34656
	v_mfma_f32_16x16x32_bf16 v[160:163], v[12:15], v[164:167], v[160:163]
	v_mfma_f32_16x16x32_bf16 v[156:159], v[28:31], v[164:167], v[156:159]
	v_mfma_f32_16x16x32_bf16 v[152:155], v[36:39], v[164:167], v[152:155]
	v_mfma_f32_16x16x32_bf16 v[236:239], v[44:47], v[164:167], v[144:147]
	v_mfma_f32_16x16x32_bf16 v[146:149], v[52:55], v[164:167], v[148:151]
	s_nop 1
	v_add_co_u32_e32 v144, vcc, s0, v230
	v_mfma_f32_16x16x32_bf16 v[136:139], v[60:63], v[164:167], v[136:139]
	v_mov_b32_e32 v151, v160
	v_mov_b32_e32 v160, v233
	v_addc_co_u32_e32 v145, vcc, 0, v231, vcc
	v_mfma_f32_16x16x32_bf16 v[140:143], v[68:71], v[164:167], v[140:143]
	v_mul_f32_e32 v166, 0x3e000000, v163
	v_mov_b32_e32 v164, v234
	v_mov_b32_e32 v165, v162
	v_mov_b32_e32 v162, v152
	v_mov_b32_e32 v163, v156
	v_mov_b32_e32 v156, v153
	v_mov_b32_e32 v152, v154
	v_mov_b32_e32 v153, v158
	v_mov_b32_e32 v158, v155
	v_mov_b32_e32 v154, v146
	v_mov_b32_e32 v155, v236
	v_mov_b32_e32 v236, v147
	v_mov_b32_e32 v146, v148
	v_mov_b32_e32 v147, v238
	v_mov_b32_e32 v238, v149
	v_mov_b32_e32 v148, v140
	v_mov_b32_e32 v149, v136
	v_mov_b32_e32 v136, v141
	v_mov_b32_e32 v140, v142
	v_mov_b32_e32 v141, v138
	v_mov_b32_e32 v138, v143
	v_pk_mul_f32 v[154:155], v[154:155], s[18:19] op_sel_hi:[1,0]
	v_pk_mul_f32 v[146:147], v[146:147], s[18:19] op_sel_hi:[1,0]
	v_pk_mul_f32 v[136:137], v[136:137], s[18:19] op_sel_hi:[1,0]
	v_mul_f32_e32 v167, 0x3e000000, v235
	v_cndmask_b32_e64 v229, v167, v226, s[54:55]
	v_pk_mul_f32 v[162:163], v[162:163], s[18:19] op_sel_hi:[1,0]
	v_pk_mul_f32 v[156:157], v[156:157], s[18:19] op_sel_hi:[1,0]
	v_pk_mul_f32 v[152:153], v[152:153], s[18:19] op_sel_hi:[1,0]
	v_pk_mul_f32 v[158:159], v[158:159], s[18:19] op_sel_hi:[1,0]
	v_cndmask_b32_e64 v157, v157, v226, s[60:61]
	v_cndmask_b32_e64 v156, v156, v226, s[62:63]
	v_pk_mul_f32 v[148:149], v[148:149], s[18:19] op_sel_hi:[1,0]
	v_pk_mul_f32 v[140:141], v[140:141], s[18:19] op_sel_hi:[1,0]
	v_pk_mul_f32 v[138:139], v[138:139], s[18:19] op_sel_hi:[1,0]
	v_cndmask_b32_e64 v141, v141, v226, s[96:97]
	v_cndmask_b32_e64 v140, v140, v226, s[4:5]
	v_cmp_lt_f32_e64 s[10:11], s39, v229
	s_waitcnt vmcnt(5)
; __device__ __forceinline__ void item_attn_cmp(LAS unsigned char* lds, const bf16_t* qkv, const bf16_t* KC, bf16_t* Yb, unsigned* selm, int it) {
;     ...
;             for (int j = 0; j < 4; ++j) { const int n = 16 * nt + 4 * g + j; const bool valid = (16 * n + 31) <= t; const float lg = valid ? z[j] * 0.125f : -1e30f; z[j] = lg; mx = fmaxf(mx, lg); }
;             s[nt] = z; }
;         mx = fmaxf(mx, __shfl_xor(mx, 16)); mx = fmaxf(mx, __shfl_xor(mx, 32));
;         float sum = 0.f;
; #pragma unroll
;         for (int nt = 0; nt < 8; ++nt)
; #pragma unroll
;             for (int j = 0; j < 4; ++j) { const float lg = s[nt][j]; const float e = (lg > -1e29f) ? __expf(lg - mx) : 0.f; s[nt][j] = e; sum += e; }
;         sum += __shfl_xor(sum, 16); sum += __shfl_xor(sum, 32);
;         const float inv = sum > 0.f ? 1.f / sum : 0.f;
; #pragma unroll
	v_lshlrev_b32_e32 v150, 16, v228
	v_mul_f32_e32 v230, 0xbfb8aa3b, v150
	v_mov_b32_e32 v150, v232
	v_pk_mul_f32 v[142:143], v[150:151], s[18:19] op_sel_hi:[1,0]
	v_pk_mul_f32 v[150:151], v[160:161], s[18:19] op_sel_hi:[1,0]
	v_pk_mul_f32 v[160:161], v[164:165], s[18:19] op_sel_hi:[1,0]
	v_cndmask_b32_e64 v232, v143, v226, s[42:43]
	v_cndmask_b32_e64 v234, v151, v226, s[46:47]
	v_cndmask_b32_e64 v228, v166, v226, s[40:41]
	v_pk_mul_f32 v[164:165], v[236:237], s[18:19] op_sel_hi:[1,0]
	v_cndmask_b32_e64 v233, v150, v226, s[48:49]
	v_cndmask_b32_e64 v236, v161, v226, s[50:51]
	v_cndmask_b32_e64 v150, v154, v226, s[74:75]
	v_cndmask_b32_e64 v154, v146, v226, s[82:83]
	v_cndmask_b32_e64 v146, v136, v226, s[94:95]
	v_max3_f32 v136, v232, s15, v234
	v_cndmask_b32_e64 v231, v142, v226, s[44:45]
	v_max3_f32 v136, v136, v236, v228
	v_cndmask_b32_e64 v235, v160, v226, s[52:53]
	v_max3_f32 v136, v136, v231, v233
	v_cndmask_b32_e64 v161, v163, v226, s[56:57]
	v_max3_f32 v136, v136, v235, v229
	v_pk_mul_f32 v[166:167], v[238:239], s[18:19] op_sel_hi:[1,0]
	v_cndmask_b32_e64 v163, v153, v226, s[64:65]
	v_cndmask_b32_e64 v238, v159, v226, s[68:69]
	v_max3_f32 v136, v136, v161, v157
	v_cndmask_b32_e64 v160, v162, v226, s[58:59]
	v_max3_f32 v136, v136, v163, v238
	v_cndmask_b32_e64 v162, v152, v226, s[66:67]
	v_cndmask_b32_e64 v237, v158, v226, s[70:71]
	v_max3_f32 v136, v136, v160, v156
	v_cndmask_b32_e64 v151, v155, v226, s[72:73]
	v_cndmask_b32_e64 v153, v165, v226, s[76:77]
	v_max3_f32 v136, v136, v162, v237
	v_cndmask_b32_e64 v155, v147, v226, s[80:81]
	v_cndmask_b32_e64 v159, v167, v226, s[84:85]
	v_max3_f32 v136, v136, v151, v153
	v_cndmask_b32_e64 v152, v164, v226, s[78:79]
	v_max3_f32 v136, v136, v155, v159
	v_cndmask_b32_e64 v158, v166, v226, s[86:87]
	v_max3_f32 v136, v136, v150, v152
	v_cndmask_b32_e64 v143, v149, v226, s[88:89]
	v_cndmask_b32_e64 v147, v137, v226, s[92:93]
	v_max3_f32 v136, v136, v154, v158
	v_cndmask_b32_e64 v149, v139, v226, s[6:7]
	v_max3_f32 v136, v136, v143, v147
	v_cndmask_b32_e64 v142, v148, v226, s[90:91]
	v_max3_f32 v136, v136, v141, v149
	v_cndmask_b32_e64 v148, v138, v226, s[8:9]
	v_max3_f32 v136, v136, v142, v146
	v_max3_f32 v136, v136, v140, v148
	ds_bpermute_b32 v137, v169, v136
	v_cmp_lt_f32_e64 s[0:1], s39, v143
	v_cmp_lt_f32_e32 vcc, s39, v228
	v_exp_f32_e32 v230, v230
	s_waitcnt lgkmcnt(0)
	v_max_f32_e32 v137, v137, v137
	v_max_f32_e32 v136, v136, v137
	ds_bpermute_b32 v137, v208, v136
	v_add_f32_e32 v246, 1.0, v230
	s_waitcnt lgkmcnt(0)
	v_max_f32_e32 v137, v137, v137
	v_max_f32_e32 v166, v136, v137
	v_sub_f32_e32 v136, v143, v166
	v_mul_f32_e32 v136, 0x3fb8aa3b, v136
	v_exp_f32_e32 v136, v136
	v_sub_f32_e32 v138, v147, v166
	v_mul_f32_e32 v138, 0x3fb8aa3b, v138
	v_exp_f32_e32 v138, v138
	v_cndmask_b32_e64 v137, 0, v136, s[0:1]
	v_sub_f32_e32 v136, v142, v166
	v_mul_f32_e32 v136, 0x3fb8aa3b, v136
	v_exp_f32_e32 v136, v136
	v_cmp_lt_f32_e64 s[0:1], s39, v142
	v_sub_f32_e32 v142, v149, v166
	v_mul_f32_e32 v142, 0x3fb8aa3b, v142
	v_cndmask_b32_e64 v136, 0, v136, s[0:1]
	v_cmp_lt_f32_e64 s[0:1], s39, v147
	v_exp_f32_e32 v142, v142
	v_sub_f32_e32 v164, v234, v166
	v_cndmask_b32_e64 v139, 0, v138, s[0:1]
	v_sub_f32_e32 v138, v146, v166
	v_mul_f32_e32 v138, 0x3fb8aa3b, v138
	v_exp_f32_e32 v138, v138
	v_cmp_lt_f32_e64 s[0:1], s39, v146
	v_sub_f32_e32 v146, v151, v166
	v_mul_f32_e32 v146, 0x3fb8aa3b, v146
	v_cndmask_b32_e64 v138, 0, v138, s[0:1]
	v_cmp_lt_f32_e64 s[0:1], s39, v141
	v_sub_f32_e32 v141, v141, v166
	v_mul_f32_e32 v141, 0x3fb8aa3b, v141
	v_exp_f32_e32 v141, v141
	v_exp_f32_e32 v146, v146
	v_mul_f32_e32 v164, 0x3fb8aa3b, v164
	v_exp_f32_e32 v164, v164
	v_cndmask_b32_e64 v141, 0, v141, s[0:1]
	v_cmp_lt_f32_e64 s[0:1], s39, v140
	v_sub_f32_e32 v140, v140, v166
	v_mul_f32_e32 v140, 0x3fb8aa3b, v140
	v_exp_f32_e32 v140, v140
	v_sub_f32_e32 v167, v236, v166
	v_mul_f32_e32 v167, 0x3fb8aa3b, v167
	v_sub_f32_e32 v228, v228, v166
	v_cndmask_b32_e64 v140, 0, v140, s[0:1]
	v_cmp_lt_f32_e64 s[0:1], s39, v149
	v_exp_f32_e32 v167, v167
	v_mul_f32_e32 v228, 0x3fb8aa3b, v228
	v_cndmask_b32_e64 v143, 0, v142, s[0:1]
	v_sub_f32_e32 v142, v148, v166
	v_mul_f32_e32 v142, 0x3fb8aa3b, v142
	v_exp_f32_e32 v142, v142
	v_cmp_lt_f32_e64 s[0:1], s39, v148
	v_sub_f32_e32 v148, v153, v166
	v_mul_f32_e32 v148, 0x3fb8aa3b, v148
	v_cndmask_b32_e64 v142, 0, v142, s[0:1]
	v_cmp_lt_f32_e64 s[0:1], s39, v151
	v_exp_f32_e32 v148, v148
	v_exp_f32_e32 v228, v228
	v_cndmask_b32_e64 v147, 0, v146, s[0:1]
	v_sub_f32_e32 v146, v150, v166
	v_mul_f32_e32 v146, 0x3fb8aa3b, v146
	v_exp_f32_e32 v146, v146
	v_cmp_lt_f32_e64 s[0:1], s39, v150
	v_sub_f32_e32 v150, v155, v166
	v_mul_f32_e32 v150, 0x3fb8aa3b, v150
	v_cndmask_b32_e64 v146, 0, v146, s[0:1]
	v_cmp_lt_f32_e64 s[0:1], s39, v153
	v_exp_f32_e32 v150, v150
	s_nop 0
	v_cndmask_b32_e64 v149, 0, v148, s[0:1]
	v_sub_f32_e32 v148, v152, v166
	v_mul_f32_e32 v148, 0x3fb8aa3b, v148
	v_exp_f32_e32 v148, v148
	v_cmp_lt_f32_e64 s[0:1], s39, v152
	v_sub_f32_e32 v152, v159, v166
	v_mul_f32_e32 v152, 0x3fb8aa3b, v152
	v_cndmask_b32_e64 v148, 0, v148, s[0:1]
	v_cmp_lt_f32_e64 s[0:1], s39, v155
	v_exp_f32_e32 v152, v152
	s_nop 0
	v_cndmask_b32_e64 v151, 0, v150, s[0:1]
	v_sub_f32_e32 v150, v154, v166
	v_mul_f32_e32 v150, 0x3fb8aa3b, v150
	v_exp_f32_e32 v150, v150
	v_cmp_lt_f32_e64 s[0:1], s39, v154
	v_sub_f32_e32 v154, v161, v166
	v_mul_f32_e32 v154, 0x3fb8aa3b, v154
	v_cndmask_b32_e64 v150, 0, v150, s[0:1]
	v_cmp_lt_f32_e64 s[0:1], s39, v159
	v_exp_f32_e32 v154, v154
	s_nop 0
	v_cndmask_b32_e64 v153, 0, v152, s[0:1]
	v_sub_f32_e32 v152, v158, v166
	v_mul_f32_e32 v152, 0x3fb8aa3b, v152
	v_exp_f32_e32 v152, v152
; __device__ __forceinline__ unsigned cvtpk(float lo, float hi) { f32x2 v = {lo, hi}; bf16x2_t b = __builtin_convertvector(v, bf16x2_t); return __builtin_bit_cast(unsigned, b); }
; #define MFMA16(a, b, c) __builtin_amdgcn_mfma_f32_16x16x32_bf16((a), (b), (c), 0, 0, 0)
; __device__ __forceinline__ bf16x8 vfrag(const LAS unsigned char* p) { const v4i16_t a = tr_read(p), b = tr_read(p + 16 * KPB); return (bf16x8){a[0], a[1], a[2], a[3], b[0], b[1], b[2], b[3]}; }
; __device__ __forceinline__ void item_attn_cmp(LAS unsigned char* lds, const bf16_t* qkv, const bf16_t* KC, bf16_t* Yb, unsigned* selm, int it) {
;     ...
;             for (int j = 0; j < 4; ++j) { const float lg = s[nt][j]; const float e = (lg > -1e29f) ? __expf(lg - mx) : 0.f; s[nt][j] = e; sum += e; }
;         sum += __shfl_xor(sum, 16); sum += __shfl_xor(sum, 32);
;         const float inv = sum > 0.f ? 1.f / sum : 0.f;
; #pragma unroll
;         for (int nt = 0; nt < 8; ++nt)
; #pragma unroll
;             for (int j = 0; j < 4; ++j) { const float p = s[nt][j] * inv; s[nt][j] = p; psum[nt][j] += p; }
;         f32x4 o[4];
; #pragma unroll
;         for (int dt = 0; dt < 4; ++dt) o[dt] = (f32x4){0.f, 0.f, 0.f, 0.f};
; #pragma unroll
;         for (int p = 0; p < 4; ++p) { u32x4 w; w.x = cvtpk(s[2 * p][0], s[2 * p][1]); w.y = cvtpk(s[2 * p][2], s[2 * p][3]); w.z = cvtpk(s[2 * p + 1][0], s[2 * p + 1][1]); w.w = cvtpk(s[2 * p + 1][2], s[2 * p + 1][3]);
;             const bf16x8 pbf = __builtin_bit_cast(bf16x8, w);
; #pragma unroll
;             for (int dt = 0; dt < 4; ++dt) { const bf16x8 vf = vfrag(Vt + (32 * p + 4 * g + (c >> 2)) * CMP_KPB + dt * 32 + (c & 3) * 8); o[dt] = MFMA16(vf, pbf, o[dt]); } }
	v_cmp_lt_f32_e64 s[0:1], s39, v158
	v_sub_f32_e32 v158, v163, v166
	v_mul_f32_e32 v158, 0x3fb8aa3b, v158
	v_cndmask_b32_e64 v152, 0, v152, s[0:1]
	v_cmp_lt_f32_e64 s[0:1], s39, v161
	v_exp_f32_e32 v158, v158
	s_nop 0
	v_cndmask_b32_e64 v155, 0, v154, s[0:1]
	v_sub_f32_e32 v154, v160, v166
	v_mul_f32_e32 v154, 0x3fb8aa3b, v154
	v_exp_f32_e32 v154, v154
	v_cmp_lt_f32_e64 s[0:1], s39, v160
	v_sub_f32_e32 v160, v238, v166
	v_mul_f32_e32 v160, 0x3fb8aa3b, v160
	v_cndmask_b32_e64 v154, 0, v154, s[0:1]
	v_cmp_lt_f32_e64 s[0:1], s39, v157
	v_sub_f32_e32 v157, v157, v166
	v_mul_f32_e32 v157, 0x3fb8aa3b, v157
	v_exp_f32_e32 v157, v157
	v_exp_f32_e32 v160, v160
	v_cndmask_b32_e64 v157, 0, v157, s[0:1]
	v_cmp_lt_f32_e64 s[0:1], s39, v156
	v_sub_f32_e32 v156, v156, v166
	v_mul_f32_e32 v156, 0x3fb8aa3b, v156
	v_exp_f32_e32 v156, v156
	s_nop 0
	v_cndmask_b32_e64 v156, 0, v156, s[0:1]
	v_cmp_lt_f32_e64 s[0:1], s39, v163
	s_nop 1
	v_cndmask_b32_e64 v159, 0, v158, s[0:1]
	v_sub_f32_e32 v158, v162, v166
	v_mul_f32_e32 v158, 0x3fb8aa3b, v158
	v_exp_f32_e32 v158, v158
	v_cmp_lt_f32_e64 s[0:1], s39, v162
	v_sub_f32_e32 v162, v232, v166
	v_mul_f32_e32 v162, 0x3fb8aa3b, v162
	v_cndmask_b32_e64 v158, 0, v158, s[0:1]
	v_cmp_lt_f32_e64 s[0:1], s39, v238
	v_exp_f32_e32 v162, v162
	s_nop 0
	v_cndmask_b32_e64 v161, 0, v160, s[0:1]
	v_sub_f32_e32 v160, v237, v166
	v_mul_f32_e32 v160, 0x3fb8aa3b, v160
	v_exp_f32_e32 v160, v160
	v_cmp_lt_f32_e64 s[0:1], s39, v237
	s_nop 1
	v_cndmask_b32_e64 v160, 0, v160, s[0:1]
	v_cmp_lt_f32_e64 s[0:1], s39, v232
	s_nop 1
	v_cndmask_b32_e64 v163, 0, v162, s[0:1]
	v_sub_f32_e32 v162, v231, v166
	v_mul_f32_e32 v162, 0x3fb8aa3b, v162
	v_exp_f32_e32 v162, v162
	v_cmp_lt_f32_e64 s[0:1], s39, v231
	v_sub_f32_e32 v231, v235, v166
	s_nop 0
	v_cndmask_b32_e64 v162, 0, v162, s[0:1]
	v_cmp_lt_f32_e64 s[0:1], s39, v234
	s_nop 1
	v_cndmask_b32_e64 v165, 0, v164, s[0:1]
	v_sub_f32_e32 v164, v233, v166
	v_mul_f32_e32 v164, 0x3fb8aa3b, v164
	v_exp_f32_e32 v164, v164
	v_sub_f32_e32 v166, v229, v166
	v_mul_f32_e32 v229, 0x3fb8aa3b, v231
	v_exp_f32_e32 v229, v229
	v_cmp_lt_f32_e64 s[0:1], s39, v233
	v_mul_f32_e32 v166, 0x3fb8aa3b, v166
	v_exp_f32_e32 v231, v166
	v_cndmask_b32_e64 v164, 0, v164, s[0:1]
	v_cmp_lt_f32_e64 s[0:1], s39, v236
	v_cndmask_b32_e64 v236, 0, v231, s[10:11]
	s_nop 0
	v_cndmask_b32_e64 v167, 0, v167, s[0:1]
	v_cmp_lt_f32_e64 s[0:1], s39, v235
	s_nop 1
	v_cndmask_b32_e64 v166, 0, v229, s[0:1]
	v_cndmask_b32_e32 v229, 0, v228, vcc
	v_add_f32_e32 v228, 0, v163
	v_add_f32_e32 v228, v165, v228
	v_add_f32_e32 v228, v167, v228
	v_add_f32_e32 v228, v229, v228
	v_add_f32_e32 v228, v162, v228
	v_add_f32_e32 v228, v164, v228
	v_add_f32_e32 v228, v166, v228
	v_add_f32_e32 v228, v236, v228
	v_add_f32_e32 v228, v155, v228
	v_add_f32_e32 v228, v157, v228
	v_add_f32_e32 v228, v159, v228
	v_add_f32_e32 v228, v161, v228
	v_add_f32_e32 v228, v154, v228
	v_add_f32_e32 v228, v156, v228
	v_add_f32_e32 v228, v158, v228
	v_add_f32_e32 v228, v160, v228
	v_add_f32_e32 v228, v147, v228
	v_add_f32_e32 v228, v149, v228
	v_add_f32_e32 v228, v151, v228
	v_add_f32_e32 v228, v153, v228
	v_add_f32_e32 v228, v146, v228
	v_add_f32_e32 v228, v148, v228
	v_add_f32_e32 v228, v150, v228
	v_add_f32_e32 v228, v152, v228
	v_add_f32_e32 v228, v137, v228
	v_add_f32_e32 v228, v139, v228
	v_add_f32_e32 v228, v141, v228
	v_add_f32_e32 v228, v143, v228
	v_add_f32_e32 v228, v136, v228
	v_add_f32_e32 v228, v138, v228
	v_add_f32_e32 v228, v140, v228
	v_add_f32_e32 v228, v142, v228
	ds_bpermute_b32 v231, v169, v228
	s_waitcnt lgkmcnt(0)
	v_add_f32_e32 v228, v228, v231
	ds_bpermute_b32 v231, v208, v228
	s_waitcnt lgkmcnt(0)
	v_add_f32_e32 v228, v228, v231
	v_div_scale_f32 v231, s[10:11], v228, v228, 1.0
	v_rcp_f32_e32 v233, v231
	v_div_scale_f32 v232, vcc, 1.0, v228, 1.0
	v_cmp_lt_f32_e64 s[0:1], 0, v228
	v_fma_f32 v234, -v231, v233, 1.0
	v_fmac_f32_e32 v233, v234, v233
	v_mul_f32_e32 v234, v232, v233
	v_fma_f32 v235, -v231, v234, v232
	v_fmac_f32_e32 v234, v235, v233
	v_fma_f32 v231, -v231, v234, v232
	v_div_fmas_f32 v231, v231, v233, v234
	v_div_fixup_f32 v228, v231, v228, 1.0
	v_cndmask_b32_e64 v228, 0, v228, s[0:1]
	v_mov_b32_e32 v237, v228
	v_pk_mul_f32 v[234:235], v[162:163], v[228:229] op_sel_hi:[1,0]
	v_pk_mul_f32 v[238:239], v[164:165], v[228:229] op_sel_hi:[1,0]
	v_pk_mul_f32 v[240:241], v[166:167], v[228:229] op_sel_hi:[1,0]
	v_pk_mul_f32 v[242:243], v[228:229], v[236:237]
	v_cvt_pk_bf16_f32 v232, v235, v239
	v_cvt_pk_bf16_f32 v234, v234, v238
	v_cvt_pk_bf16_f32 v233, v241, v243
	v_cvt_pk_bf16_f32 v235, v240, v242
	v_pk_mul_f32 v[238:239], v[154:155], v[228:229] op_sel_hi:[1,0]
	v_pk_mul_f32 v[240:241], v[156:157], v[228:229] op_sel_hi:[1,0]
	v_mfma_f32_16x16x32_bf16 v[72:75], v[72:75], v[232:235], 0
	v_mul_f32_e64 v242, v158, v228
	v_mul_f32_e64 v243, v159, v228
	v_pk_mul_f32 v[244:245], v[160:161], v[228:229] op_sel_hi:[1,0]
	v_cvt_pk_bf16_f32 v230, v239, v241
	v_mfma_f32_16x16x32_bf16 v[80:83], v[80:83], v[232:235], 0
	v_cvt_pk_bf16_f32 v231, v243, v245
	v_pk_fma_f32 v[200:201], v[162:163], v[228:229], v[200:201] op_sel_hi:[1,0,1]
	v_pk_mul_f32 v[162:163], v[152:153], v[228:229] op_sel_hi:[1,0]
	v_mfma_f32_16x16x32_bf16 v[76:79], v[76:79], v[232:235], 0
	v_fma_f32 v202, v164, v228, v202
	v_fma_f32 v203, v165, v228, v203
	v_pk_fma_f32 v[204:205], v[166:167], v[228:229], v[204:205] op_sel_hi:[1,0,1]
	v_pk_fma_f32 v[192:193], v[154:155], v[228:229], v[192:193] op_sel_hi:[1,0,1]
	v_mfma_f32_16x16x32_bf16 v[120:123], v[120:123], v[232:235], 0
	v_cvt_pk_bf16_f32 v232, v238, v240
	v_cvt_pk_bf16_f32 v233, v242, v244
	v_pk_fma_f32 v[194:195], v[156:157], v[228:229], v[194:195] op_sel_hi:[1,0,1]
; #define LAS __attribute__((address_space(3)))
; __device__ __forceinline__ unsigned cvtpk(float lo, float hi) { f32x2 v = {lo, hi}; bf16x2_t b = __builtin_convertvector(v, bf16x2_t); return __builtin_bit_cast(unsigned, b); }
; __device__ __forceinline__ void store_row16(bf16_t* rowp, int g, const u32x2 (&pk)[4]) {
;     const int par = g & 1;
; #pragma unroll
;     for (int pr = 0; pr < 2; ++pr) {
;         const auto sx = __builtin_amdgcn_permlane16_swap(pk[2 * pr].x, pk[2 * pr + 1].x, false, false);
;         const auto sy = __builtin_amdgcn_permlane16_swap(pk[2 * pr].y, pk[2 * pr + 1].y, false, false);
;         u32x4 w; w.x = sx[0]; w.y = sy[0]; w.z = sx[1]; w.w = sy[1];
;         *(u32x4*)(rowp + 16 * (2 * pr + par) + 4 * (g - par)) = w; }
; __device__ __forceinline__ void item_attn_cmp(LAS unsigned char* lds, const bf16_t* qkv, const bf16_t* KC, bf16_t* Yb, unsigned* selm, int it) {
;     ...
;         for (int p = 0; p < 4; ++p) { u32x4 w; w.x = cvtpk(s[2 * p][0], s[2 * p][1]); w.y = cvtpk(s[2 * p][2], s[2 * p][3]); w.z = cvtpk(s[2 * p + 1][0], s[2 * p + 1][1]); w.w = cvtpk(s[2 * p + 1][2], s[2 * p + 1][3]);
;             const bf16x8 pbf = __builtin_bit_cast(bf16x8, w);
; #pragma unroll
;             for (int dt = 0; dt < 4; ++dt) { const bf16x8 vf = vfrag(Vt + (32 * p + 4 * g + (c >> 2)) * CMP_KPB + dt * 32 + (c & 3) * 8); o[dt] = MFMA16(vf, pbf, o[dt]); } }
;         const float g0 = sigmoidf_(bf2f(qkv[row * QP + C_BG + h]));
;         { u32x2 pk[4];
; #pragma unroll
;           for (int dt = 0; dt < 4; ++dt) { pk[dt].x = cvtpk(o[dt][0] * g0, o[dt][1] * g0); pk[dt].y = cvtpk(o[dt][2] * g0, o[dt][3] * g0); }
;           store_row16(Yb + row * 512 + h * 64, g, pk); }
;     }
;     float imp[8], sh3[8];
; #pragma unroll
;     for (int nt = 0; nt < 8; ++nt) sh3[nt] = __shfl(psum[nt][3], (lane + 48) & 63);
; #pragma unroll
;     for (int nt = 0; nt < 8; ++nt) { const float prev = (g > 0) ? sh3[nt] : (nt > 0 ? sh3[nt > 0 ? nt - 1 : 0] : 0.f); imp[nt] = (psum[nt][0] + psum[nt][1]) + (psum[nt][2] + psum[nt][3]) + prev; }
;     const int cur = t >> 6; const int nforced = cur >= 2 ? 3 : cur + 1; const int nfree = 16 - nforced;
;     LAS float* impl = (LAS float*)(lds + CMP_IMP) + (wid * 16 + c) * 33;
; #pragma unroll
;     for (int nt = 0; nt < 8; ++nt) impl[4 * nt + g] = imp[nt];
	v_pk_fma_f32 v[196:197], v[158:159], v[228:229], v[196:197] op_sel_hi:[1,0,1]
	v_mfma_f32_16x16x32_bf16 v[72:75], v[116:119], v[230:233], v[72:75]
	v_mul_f32_e64 v118, v150, v228
	v_mul_f32_e64 v119, v151, v228
	v_rcp_f32_e32 v116, v246
	v_pk_fma_f32 v[198:199], v[160:161], v[228:229], v[198:199] op_sel_hi:[1,0,1]
	v_mfma_f32_16x16x32_bf16 v[80:83], v[112:115], v[230:233], v[80:83]
	v_mul_f32_e64 v112, v146, v228
	v_mul_f32_e64 v113, v147, v228
	v_pk_mul_f32 v[114:115], v[148:149], v[228:229] op_sel_hi:[1,0]
	v_pk_fma_f32 v[182:183], v[146:147], v[228:229], v[182:183] op_sel_hi:[1,0,1]
	v_mfma_f32_16x16x32_bf16 v[76:79], v[108:111], v[230:233], v[76:79]
	v_cvt_pk_bf16_f32 v108, v113, v115
	v_cvt_pk_bf16_f32 v109, v119, v163
	v_cvt_pk_bf16_f32 v110, v112, v114
	v_mfma_f32_16x16x32_bf16 v[104:107], v[104:107], v[230:233], v[120:123]
	v_cvt_pk_bf16_f32 v111, v118, v162
	v_pk_fma_f32 v[186:187], v[148:149], v[228:229], v[186:187] op_sel_hi:[1,0,1]
	v_pk_fma_f32 v[188:189], v[150:151], v[228:229], v[188:189] op_sel_hi:[1,0,1]
	v_mfma_f32_16x16x32_bf16 v[72:75], v[100:103], v[108:111], v[72:75]
	v_mul_f32_e64 v100, v140, v228
	v_mul_f32_e64 v101, v141, v228
	v_pk_mul_f32 v[102:103], v[142:143], v[228:229] op_sel_hi:[1,0]
	v_pk_fma_f32 v[190:191], v[152:153], v[228:229], v[190:191] op_sel_hi:[1,0,1]
	v_mfma_f32_16x16x32_bf16 v[80:83], v[96:99], v[108:111], v[80:83]
	v_mul_f32_e64 v96, v136, v228
	v_mul_f32_e64 v97, v137, v228
	v_pk_mul_f32 v[98:99], v[138:139], v[228:229] op_sel_hi:[1,0]
	v_pk_fma_f32 v[170:171], v[136:137], v[228:229], v[170:171] op_sel_hi:[1,0,1]
	v_mfma_f32_16x16x32_bf16 v[76:79], v[92:95], v[108:111], v[76:79]
	v_cvt_pk_bf16_f32 v92, v97, v99
	v_cvt_pk_bf16_f32 v93, v101, v103
	v_cvt_pk_bf16_f32 v94, v96, v98
	v_mfma_f32_16x16x32_bf16 v[88:91], v[88:91], v[108:111], v[104:107]
	v_cvt_pk_bf16_f32 v95, v100, v102
	v_pk_fma_f32 v[174:175], v[138:139], v[228:229], v[174:175] op_sel_hi:[1,0,1]
	v_pk_fma_f32 v[176:177], v[140:141], v[228:229], v[176:177] op_sel_hi:[1,0,1]
	v_mfma_f32_16x16x32_bf16 v[72:75], v[84:87], v[92:95], v[72:75]
	v_fma_f32 v178, v142, v228, v178
	v_fma_f32 v179, v143, v228, v179
	v_pk_fma_f32 v[206:207], v[228:229], v[236:237], v[206:207]
	v_mfma_f32_16x16x32_bf16 v[80:83], v[124:127], v[92:95], v[80:83]
	v_mfma_f32_16x16x32_bf16 v[76:79], v[128:131], v[92:95], v[76:79]
	s_nop 2
	v_mul_f32_e64 v72, v72, v116
	v_mul_f32_e64 v73, v73, v116
	v_pk_mul_f32 v[74:75], v[74:75], v[116:117] op_sel_hi:[1,0]
	s_nop 0
	v_pk_mul_f32 v[80:81], v[80:81], v[116:117] op_sel_hi:[1,0]
	v_mfma_f32_16x16x32_bf16 v[84:87], v[132:135], v[92:95], v[88:91]
	v_mul_f32_e64 v82, v82, v116
	v_mul_f32_e64 v83, v83, v116
	v_pk_mul_f32 v[76:77], v[76:77], v[116:117] op_sel_hi:[1,0]
	v_pk_mul_f32 v[78:79], v[78:79], v[116:117] op_sel_hi:[1,0]
	v_cvt_pk_bf16_f32 v72, v72, v73
	v_cvt_pk_bf16_f32 v73, v74, v75
	s_nop 1
	v_pk_mul_f32 v[84:85], v[84:85], v[116:117] op_sel_hi:[1,0]
	v_pk_mul_f32 v[86:87], v[86:87], v[116:117] op_sel_hi:[1,0]
	v_cvt_pk_bf16_f32 v74, v80, v81
	v_cvt_pk_bf16_f32 v75, v82, v83
	v_cvt_pk_bf16_f32 v76, v76, v77
	v_cvt_pk_bf16_f32 v77, v78, v79
	v_cvt_pk_bf16_f32 v78, v84, v85
	v_cvt_pk_bf16_f32 v79, v86, v87
	v_permlane16_swap_b32_e32 v72, v74
	v_permlane16_swap_b32_e32 v73, v75
	v_permlane16_swap_b32_e32 v76, v78
	v_permlane16_swap_b32_e32 v77, v79
	global_store_dwordx4 v[144:145], v[72:75], off
	global_store_dwordx4 v[144:145], v[76:79], off offset:64
	s_cbranch_scc0 .LBB0_359
	v_add_u32_e32 v1, 48, v1
	v_and_b32_e32 v1, 63, v1
	v_and_or_b32 v1, v217, 64, v1
	v_lshlrev_b32_e32 v1, 2, v1
	ds_bpermute_b32 v16, v1, v207
	ds_bpermute_b32 v18, v1, v206
	ds_bpermute_b32 v19, v1, v199
	ds_bpermute_b32 v28, v1, v198
	ds_bpermute_b32 v29, v1, v191
	ds_bpermute_b32 v30, v1, v190
	ds_bpermute_b32 v31, v1, v179
	ds_bpermute_b32 v1, v1, v178
	v_cmp_gt_u32_e32 vcc, 16, v212
	v_pk_add_f32 v[8:9], v[200:201], v[202:203]
	v_pk_add_f32 v[10:11], v[204:205], v[206:207]
	v_pk_add_f32 v[12:13], v[192:193], v[194:195]
	v_pk_add_f32 v[14:15], v[196:197], v[198:199]
	v_pk_add_f32 v[8:9], v[8:9], v[10:11]
	s_waitcnt lgkmcnt(6)
	v_cndmask_b32_e32 v10, v18, v16, vcc
	v_cndmask_b32_e64 v11, v16, 0, vcc
	v_pk_add_f32 v[20:21], v[182:183], v[186:187]
	v_pk_add_f32 v[22:23], v[188:189], v[190:191]
	v_pk_add_f32 v[16:17], v[8:9], v[10:11]
	v_pk_add_f32 v[8:9], v[12:13], v[14:15]
	s_waitcnt lgkmcnt(5)
	v_cndmask_b32_e32 v11, v19, v18, vcc
	s_waitcnt lgkmcnt(4)
	v_cndmask_b32_e32 v10, v28, v19, vcc
	v_pk_add_f32 v[18:19], v[8:9], v[10:11]
	v_pk_add_f32 v[8:9], v[20:21], v[22:23]
	s_waitcnt lgkmcnt(3)
	v_cndmask_b32_e32 v11, v29, v28, vcc
	s_waitcnt lgkmcnt(2)
	v_cndmask_b32_e32 v10, v30, v29, vcc
	v_pk_add_f32 v[20:21], v[8:9], v[10:11]
	s_waitcnt lgkmcnt(0)
	v_cndmask_b32_e32 v8, v1, v31, vcc
	v_or_b32_e32 v1, v3, v209
	s_movk_i32 s0, 0x84
	v_mul_lo_u32 v52, v1, s0
	v_lshlrev_b32_e32 v1, 2, v168
	v_pk_add_f32 v[24:25], v[170:171], v[174:175]
	v_pk_add_f32 v[26:27], v[176:177], v[178:179]
	v_add3_u32 v1, 0, v52, v1
	v_cndmask_b32_e32 v9, v31, v30, vcc
	v_pk_add_f32 v[10:11], v[24:25], v[26:27]
	v_add_u32_e32 v1, 0x9000, v1
	v_pk_add_f32 v[22:23], v[10:11], v[8:9]
	ds_write2_b32 v1, v17, v16 offset1:4
	ds_write2_b32 v1, v19, v18 offset0:8 offset1:12
	ds_write2_b32 v1, v21, v20 offset0:16 offset1:20
	ds_write2_b32 v1, v23, v22 offset0:24 offset1:28
	s_waitcnt lgkmcnt(0)
	v_ashrrev_i32_e32 v51, 6, v211
	s_mov_b32 s86, 0xf149f2ca
	v_add_u32_e32 v54, -2, v51
	v_cmp_lt_i32_e64 s[0:1], 2, v51
	v_add_u32_e32 v55, -1, v51
	v_or_b32_e32 v14, 4, v168
	v_or_b32_e32 v11, 8, v168
	v_or_b32_e32 v12, 12, v168
	v_or_b32_e32 v9, 16, v168
	v_or_b32_e32 v10, 20, v168
	v_or_b32_e32 v3, 24, v168
	v_or_b32_e32 v8, 28, v168
	s_and_saveexec_b64 s[4:5], s[0:1]
	s_xor_b64 s[42:43], exec, s[4:5]
	s_movk_i32 s84, 0x90
	s_movk_i32 s85, 0x1c30
	s_cbranch_execz .LBB0_372
	v_or_b32_e32 v14, 4, v168
	v_mov_b32_e32 v1, v168
	v_cmp_lt_u32_e64 s[0:1], 1, v54
	s_mov_b64 s[4:5], 0
	s_and_saveexec_b64 s[6:7], s[0:1]
	s_xor_b64 s[44:45], exec, s[6:7]
	s_cbranch_execnz .LBB0_364
	s_andn2_saveexec_b64 s[0:1], s[44:45]
	s_cbranch_execnz .LBB0_367
